# x3 W2 section hand-pipelined (A fragments prefetched one kk ahead into the window registers, xpb loads hoisted into the Toeplitz tail) on top of the lockstep gelu epilogue
# speedup vs baseline: 1.0075x; 1.0075x over previous
.Lmy_x3_epi:
	global_load_dwordx2 v[98:99], v[2:3], off
	v_lshl_add_u64 v[2:3], v[128:129], 0, v[0:1]
	v_lshlrev_b32_e32 v0, 13, v201
	global_load_dwordx2 v[96:97], v[2:3], off
	v_lshl_add_u64 v[2:3], v[128:129], 0, v[0:1]
	v_lshlrev_b32_e32 v0, 13, v200
	global_load_dwordx2 v[94:95], v[2:3], off
	v_lshl_add_u64 v[2:3], v[128:129], 0, v[0:1]
	v_lshlrev_b32_e32 v0, 13, v199
	global_load_dwordx2 v[92:93], v[2:3], off
	v_lshl_add_u64 v[2:3], v[128:129], 0, v[0:1]
	v_lshlrev_b32_e32 v0, 13, v198
	global_load_dwordx2 v[90:91], v[2:3], off
	v_lshl_add_u64 v[2:3], v[128:129], 0, v[0:1]
	v_lshlrev_b32_e32 v0, 13, v197
	global_load_dwordx2 v[88:89], v[2:3], off
	v_lshl_add_u64 v[2:3], v[128:129], 0, v[0:1]
	v_lshlrev_b32_e32 v0, 13, v196
	global_load_dwordx2 v[86:87], v[2:3], off
	v_lshl_add_u64 v[2:3], v[128:129], 0, v[0:1]
	v_lshlrev_b32_e32 v0, 13, v195
	global_load_dwordx2 v[84:85], v[2:3], off
	v_lshl_add_u64 v[2:3], v[128:129], 0, v[0:1]
	v_lshlrev_b32_e32 v0, 13, v194
	global_load_dwordx2 v[82:83], v[2:3], off
	v_lshl_add_u64 v[2:3], v[128:129], 0, v[0:1]
	v_lshlrev_b32_e32 v0, 13, v193
	global_load_dwordx2 v[80:81], v[2:3], off
	v_lshl_add_u64 v[2:3], v[128:129], 0, v[0:1]
	v_lshlrev_b32_e32 v0, 13, v123
	global_load_dwordx2 v[78:79], v[2:3], off
	v_lshl_add_u64 v[2:3], v[128:129], 0, v[0:1]
	v_lshlrev_b32_e32 v0, 13, v121
	global_load_dwordx2 v[76:77], v[2:3], off
	v_lshl_add_u64 v[2:3], v[128:129], 0, v[0:1]
	v_lshlrev_b32_e32 v0, 13, v103
	global_load_dwordx2 v[74:75], v[2:3], off
	v_lshl_add_u64 v[2:3], v[128:129], 0, v[0:1]
	v_lshlrev_b32_e32 v0, 13, v102
	global_load_dwordx2 v[72:73], v[2:3], off
	v_lshl_add_u64 v[2:3], v[128:129], 0, v[0:1]
	global_load_dwordx2 v[2:3], v[2:3], off
	s_waitcnt vmcnt(15)
	v_lshlrev_b32_e32 v204, 16, v100
	v_and_b32_e32 v205, 0xffff0000, v100
	v_lshlrev_b32_e32 v206, 16, v101
	v_and_b32_e32 v207, 0xffff0000, v101
	v_fma_f32 v68, v4, v204, v68
	v_fma_f32 v69, v5, v205, v69
	v_fma_f32 v70, v6, v206, v70
	v_fma_f32 v71, v7, v207, v71
	v_mul_f32_e32 v204, 0x3d372713, v68
	v_mul_f32_e32 v205, 0x3d372713, v69
	v_mul_f32_e32 v206, 0x3d372713, v70
	v_mul_f32_e32 v207, 0x3d372713, v71
	v_mul_f32_e32 v204, v68, v204
	v_mul_f32_e32 v205, v69, v205
	v_mul_f32_e32 v206, v70, v206
	v_mul_f32_e32 v207, v71, v207
	v_fma_f32 v204, v68, v204, v68
	v_fma_f32 v205, v69, v205, v69
	v_fma_f32 v206, v70, v206, v70
	v_fma_f32 v207, v71, v207, v71
	v_mul_f32_e32 v204, 0xbfcc422a, v204
	v_mul_f32_e32 v205, 0xbfcc422a, v205
	v_mul_f32_e32 v206, 0xbfcc422a, v206
	v_mul_f32_e32 v207, 0xbfcc422a, v207
	v_mul_f32_e32 v204, 0x3fb8aa3b, v204
	v_mul_f32_e32 v205, 0x3fb8aa3b, v205
	v_mul_f32_e32 v206, 0x3fb8aa3b, v206
	v_mul_f32_e32 v207, 0x3fb8aa3b, v207
	v_exp_f32_e32 v204, v204
	v_exp_f32_e32 v205, v205
	v_exp_f32_e32 v206, v206
	v_exp_f32_e32 v207, v207
	v_add_f32_e32 v204, 1.0, v204
	v_add_f32_e32 v205, 1.0, v205
	v_add_f32_e32 v206, 1.0, v206
	v_add_f32_e32 v207, 1.0, v207
	v_rcp_f32_e32 v204, v204
	v_rcp_f32_e32 v205, v205
	v_rcp_f32_e32 v206, v206
	v_rcp_f32_e32 v207, v207
	v_mul_f32_e32 v204, v68, v204
	v_mul_f32_e32 v205, v69, v205
	v_mul_f32_e32 v206, v70, v206
	v_mul_f32_e32 v207, v71, v207
	v_cvt_pk_bf16_f32 v208, v204, v205
	v_cvt_pk_bf16_f32 v209, v206, v207
	v_lshlrev_b32_e32 v0, 12, v148
	v_lshl_add_u64 v[210:211], v[132:133], 0, v[0:1]
	global_store_dwordx2 v[210:211], v[208:209], off
	s_waitcnt vmcnt(15)
	v_lshlrev_b32_e32 v204, 16, v98
	v_and_b32_e32 v205, 0xffff0000, v98
	v_lshlrev_b32_e32 v206, 16, v99
	v_and_b32_e32 v207, 0xffff0000, v99
	v_fma_f32 v64, v4, v204, v64
	v_fma_f32 v65, v5, v205, v65
	v_fma_f32 v66, v6, v206, v66
	v_fma_f32 v67, v7, v207, v67
	v_mul_f32_e32 v204, 0x3d372713, v64
	v_mul_f32_e32 v205, 0x3d372713, v65
	v_mul_f32_e32 v206, 0x3d372713, v66
	v_mul_f32_e32 v207, 0x3d372713, v67
	v_mul_f32_e32 v204, v64, v204
	v_mul_f32_e32 v205, v65, v205
	v_mul_f32_e32 v206, v66, v206
	v_mul_f32_e32 v207, v67, v207
	v_fma_f32 v204, v64, v204, v64
	v_fma_f32 v205, v65, v205, v65
	v_fma_f32 v206, v66, v206, v66
	v_fma_f32 v207, v67, v207, v67
	v_mul_f32_e32 v204, 0xbfcc422a, v204
	v_mul_f32_e32 v205, 0xbfcc422a, v205
	v_mul_f32_e32 v206, 0xbfcc422a, v206
	v_mul_f32_e32 v207, 0xbfcc422a, v207
	v_mul_f32_e32 v204, 0x3fb8aa3b, v204
	v_mul_f32_e32 v205, 0x3fb8aa3b, v205
	v_mul_f32_e32 v206, 0x3fb8aa3b, v206
	v_mul_f32_e32 v207, 0x3fb8aa3b, v207
	v_exp_f32_e32 v204, v204
	v_exp_f32_e32 v205, v205
	v_exp_f32_e32 v206, v206
	v_exp_f32_e32 v207, v207
	v_add_f32_e32 v204, 1.0, v204
	v_add_f32_e32 v205, 1.0, v205
	v_add_f32_e32 v206, 1.0, v206
	v_add_f32_e32 v207, 1.0, v207
	v_rcp_f32_e32 v204, v204
	v_rcp_f32_e32 v205, v205
	v_rcp_f32_e32 v206, v206
	v_rcp_f32_e32 v207, v207
	v_mul_f32_e32 v204, v64, v204
	v_mul_f32_e32 v205, v65, v205
	v_mul_f32_e32 v206, v66, v206
	v_mul_f32_e32 v207, v67, v207
	v_cvt_pk_bf16_f32 v208, v204, v205
	v_cvt_pk_bf16_f32 v209, v206, v207
	v_lshlrev_b32_e32 v0, 12, v203
	v_lshl_add_u64 v[210:211], v[132:133], 0, v[0:1]
	global_store_dwordx2 v[210:211], v[208:209], off
	s_waitcnt vmcnt(15)
	v_lshlrev_b32_e32 v204, 16, v96
	v_and_b32_e32 v205, 0xffff0000, v96
	v_lshlrev_b32_e32 v206, 16, v97
	v_and_b32_e32 v207, 0xffff0000, v97
	v_fma_f32 v60, v4, v204, v60
	v_fma_f32 v61, v5, v205, v61
	v_fma_f32 v62, v6, v206, v62
	v_fma_f32 v63, v7, v207, v63
	v_mul_f32_e32 v204, 0x3d372713, v60
	v_mul_f32_e32 v205, 0x3d372713, v61
	v_mul_f32_e32 v206, 0x3d372713, v62
	v_mul_f32_e32 v207, 0x3d372713, v63
	v_mul_f32_e32 v204, v60, v204
	v_mul_f32_e32 v205, v61, v205
	v_mul_f32_e32 v206, v62, v206
	v_mul_f32_e32 v207, v63, v207
	v_fma_f32 v204, v60, v204, v60
	v_fma_f32 v205, v61, v205, v61
	v_fma_f32 v206, v62, v206, v62
	v_fma_f32 v207, v63, v207, v63
	v_mul_f32_e32 v204, 0xbfcc422a, v204
	v_mul_f32_e32 v205, 0xbfcc422a, v205
	v_mul_f32_e32 v206, 0xbfcc422a, v206
	v_mul_f32_e32 v207, 0xbfcc422a, v207
	v_mul_f32_e32 v204, 0x3fb8aa3b, v204
	v_mul_f32_e32 v205, 0x3fb8aa3b, v205
	v_mul_f32_e32 v206, 0x3fb8aa3b, v206
	v_mul_f32_e32 v207, 0x3fb8aa3b, v207
	v_exp_f32_e32 v204, v204
	v_exp_f32_e32 v205, v205
	v_exp_f32_e32 v206, v206
	v_exp_f32_e32 v207, v207
	v_add_f32_e32 v204, 1.0, v204
	v_add_f32_e32 v205, 1.0, v205
	v_add_f32_e32 v206, 1.0, v206
	v_add_f32_e32 v207, 1.0, v207
	v_rcp_f32_e32 v204, v204
	v_rcp_f32_e32 v205, v205
	v_rcp_f32_e32 v206, v206
	v_rcp_f32_e32 v207, v207
	v_mul_f32_e32 v204, v60, v204
	v_mul_f32_e32 v205, v61, v205
	v_mul_f32_e32 v206, v62, v206
	v_mul_f32_e32 v207, v63, v207
	v_cvt_pk_bf16_f32 v208, v204, v205
	v_cvt_pk_bf16_f32 v209, v206, v207
	v_lshlrev_b32_e32 v0, 12, v202
	v_lshl_add_u64 v[210:211], v[132:133], 0, v[0:1]
	global_store_dwordx2 v[210:211], v[208:209], off
	s_waitcnt vmcnt(15)
	v_lshlrev_b32_e32 v204, 16, v94
	v_and_b32_e32 v205, 0xffff0000, v94
	v_lshlrev_b32_e32 v206, 16, v95
	v_and_b32_e32 v207, 0xffff0000, v95
	v_fma_f32 v56, v4, v204, v56
	v_fma_f32 v57, v5, v205, v57
	v_fma_f32 v58, v6, v206, v58
	v_fma_f32 v59, v7, v207, v59
	v_mul_f32_e32 v204, 0x3d372713, v56
	v_mul_f32_e32 v205, 0x3d372713, v57
	v_mul_f32_e32 v206, 0x3d372713, v58
	v_mul_f32_e32 v207, 0x3d372713, v59
	v_mul_f32_e32 v204, v56, v204
	v_mul_f32_e32 v205, v57, v205
	v_mul_f32_e32 v206, v58, v206
	v_mul_f32_e32 v207, v59, v207
	v_fma_f32 v204, v56, v204, v56
	v_fma_f32 v205, v57, v205, v57
	v_fma_f32 v206, v58, v206, v58
	v_fma_f32 v207, v59, v207, v59
	v_mul_f32_e32 v204, 0xbfcc422a, v204
	v_mul_f32_e32 v205, 0xbfcc422a, v205
	v_mul_f32_e32 v206, 0xbfcc422a, v206
	v_mul_f32_e32 v207, 0xbfcc422a, v207
	v_mul_f32_e32 v204, 0x3fb8aa3b, v204
	v_mul_f32_e32 v205, 0x3fb8aa3b, v205
	v_mul_f32_e32 v206, 0x3fb8aa3b, v206
	v_mul_f32_e32 v207, 0x3fb8aa3b, v207
	v_exp_f32_e32 v204, v204
	v_exp_f32_e32 v205, v205
	v_exp_f32_e32 v206, v206
	v_exp_f32_e32 v207, v207
	v_add_f32_e32 v204, 1.0, v204
	v_add_f32_e32 v205, 1.0, v205
	v_add_f32_e32 v206, 1.0, v206
	v_add_f32_e32 v207, 1.0, v207
	v_rcp_f32_e32 v204, v204
	v_rcp_f32_e32 v205, v205
	v_rcp_f32_e32 v206, v206
	v_rcp_f32_e32 v207, v207
	v_mul_f32_e32 v204, v56, v204
	v_mul_f32_e32 v205, v57, v205
	v_mul_f32_e32 v206, v58, v206
	v_mul_f32_e32 v207, v59, v207
	v_cvt_pk_bf16_f32 v208, v204, v205
	v_cvt_pk_bf16_f32 v209, v206, v207
	v_lshlrev_b32_e32 v0, 12, v201
	v_lshl_add_u64 v[210:211], v[132:133], 0, v[0:1]
	global_store_dwordx2 v[210:211], v[208:209], off
	s_waitcnt vmcnt(15)
	v_lshlrev_b32_e32 v204, 16, v92
	v_and_b32_e32 v205, 0xffff0000, v92
	v_lshlrev_b32_e32 v206, 16, v93
	v_and_b32_e32 v207, 0xffff0000, v93
	v_fma_f32 v52, v4, v204, v52
	v_fma_f32 v53, v5, v205, v53
	v_fma_f32 v54, v6, v206, v54
	v_fma_f32 v55, v7, v207, v55
	v_mul_f32_e32 v204, 0x3d372713, v52
	v_mul_f32_e32 v205, 0x3d372713, v53
	v_mul_f32_e32 v206, 0x3d372713, v54
	v_mul_f32_e32 v207, 0x3d372713, v55
	v_mul_f32_e32 v204, v52, v204
	v_mul_f32_e32 v205, v53, v205
	v_mul_f32_e32 v206, v54, v206
	v_mul_f32_e32 v207, v55, v207
	v_fma_f32 v204, v52, v204, v52
	v_fma_f32 v205, v53, v205, v53
	v_fma_f32 v206, v54, v206, v54
	v_fma_f32 v207, v55, v207, v55
	v_mul_f32_e32 v204, 0xbfcc422a, v204
	v_mul_f32_e32 v205, 0xbfcc422a, v205
	v_mul_f32_e32 v206, 0xbfcc422a, v206
	v_mul_f32_e32 v207, 0xbfcc422a, v207
	v_mul_f32_e32 v204, 0x3fb8aa3b, v204
	v_mul_f32_e32 v205, 0x3fb8aa3b, v205
	v_mul_f32_e32 v206, 0x3fb8aa3b, v206
	v_mul_f32_e32 v207, 0x3fb8aa3b, v207
	v_exp_f32_e32 v204, v204
	v_exp_f32_e32 v205, v205
	v_exp_f32_e32 v206, v206
	v_exp_f32_e32 v207, v207
	v_add_f32_e32 v204, 1.0, v204
	v_add_f32_e32 v205, 1.0, v205
	v_add_f32_e32 v206, 1.0, v206
	v_add_f32_e32 v207, 1.0, v207
	v_rcp_f32_e32 v204, v204
	v_rcp_f32_e32 v205, v205
	v_rcp_f32_e32 v206, v206
	v_rcp_f32_e32 v207, v207
	v_mul_f32_e32 v204, v52, v204
	v_mul_f32_e32 v205, v53, v205
	v_mul_f32_e32 v206, v54, v206
	v_mul_f32_e32 v207, v55, v207
	v_cvt_pk_bf16_f32 v208, v204, v205
	v_cvt_pk_bf16_f32 v209, v206, v207
	v_lshlrev_b32_e32 v0, 12, v200
	v_lshl_add_u64 v[210:211], v[132:133], 0, v[0:1]
	global_store_dwordx2 v[210:211], v[208:209], off
	s_waitcnt vmcnt(15)
	v_lshlrev_b32_e32 v204, 16, v90
	v_and_b32_e32 v205, 0xffff0000, v90
	v_lshlrev_b32_e32 v206, 16, v91
	v_and_b32_e32 v207, 0xffff0000, v91
	v_fma_f32 v48, v4, v204, v48
	v_fma_f32 v49, v5, v205, v49
	v_fma_f32 v50, v6, v206, v50
	v_fma_f32 v51, v7, v207, v51
	v_mul_f32_e32 v204, 0x3d372713, v48
	v_mul_f32_e32 v205, 0x3d372713, v49
	v_mul_f32_e32 v206, 0x3d372713, v50
	v_mul_f32_e32 v207, 0x3d372713, v51
	v_mul_f32_e32 v204, v48, v204
	v_mul_f32_e32 v205, v49, v205
	v_mul_f32_e32 v206, v50, v206
	v_mul_f32_e32 v207, v51, v207
	v_fma_f32 v204, v48, v204, v48
	v_fma_f32 v205, v49, v205, v49
	v_fma_f32 v206, v50, v206, v50
	v_fma_f32 v207, v51, v207, v51
	v_mul_f32_e32 v204, 0xbfcc422a, v204
	v_mul_f32_e32 v205, 0xbfcc422a, v205
	v_mul_f32_e32 v206, 0xbfcc422a, v206
	v_mul_f32_e32 v207, 0xbfcc422a, v207
	v_mul_f32_e32 v204, 0x3fb8aa3b, v204
	v_mul_f32_e32 v205, 0x3fb8aa3b, v205
	v_mul_f32_e32 v206, 0x3fb8aa3b, v206
	v_mul_f32_e32 v207, 0x3fb8aa3b, v207
	v_exp_f32_e32 v204, v204
	v_exp_f32_e32 v205, v205
	v_exp_f32_e32 v206, v206
	v_exp_f32_e32 v207, v207
	v_add_f32_e32 v204, 1.0, v204
	v_add_f32_e32 v205, 1.0, v205
	v_add_f32_e32 v206, 1.0, v206
	v_add_f32_e32 v207, 1.0, v207
	v_rcp_f32_e32 v204, v204
	v_rcp_f32_e32 v205, v205
	v_rcp_f32_e32 v206, v206
	v_rcp_f32_e32 v207, v207
	v_mul_f32_e32 v204, v48, v204
	v_mul_f32_e32 v205, v49, v205
	v_mul_f32_e32 v206, v50, v206
	v_mul_f32_e32 v207, v51, v207
	v_cvt_pk_bf16_f32 v208, v204, v205
	v_cvt_pk_bf16_f32 v209, v206, v207
	v_lshlrev_b32_e32 v0, 12, v199
	v_lshl_add_u64 v[210:211], v[132:133], 0, v[0:1]
	global_store_dwordx2 v[210:211], v[208:209], off
	s_waitcnt vmcnt(15)
	v_lshlrev_b32_e32 v204, 16, v88
	v_and_b32_e32 v205, 0xffff0000, v88
	v_lshlrev_b32_e32 v206, 16, v89
	v_and_b32_e32 v207, 0xffff0000, v89
	v_fma_f32 v44, v4, v204, v44
	v_fma_f32 v45, v5, v205, v45
	v_fma_f32 v46, v6, v206, v46
	v_fma_f32 v47, v7, v207, v47
	v_mul_f32_e32 v204, 0x3d372713, v44
	v_mul_f32_e32 v205, 0x3d372713, v45
	v_mul_f32_e32 v206, 0x3d372713, v46
	v_mul_f32_e32 v207, 0x3d372713, v47
	v_mul_f32_e32 v204, v44, v204
	v_mul_f32_e32 v205, v45, v205
	v_mul_f32_e32 v206, v46, v206
	v_mul_f32_e32 v207, v47, v207
	v_fma_f32 v204, v44, v204, v44
	v_fma_f32 v205, v45, v205, v45
	v_fma_f32 v206, v46, v206, v46
	v_fma_f32 v207, v47, v207, v47
	v_mul_f32_e32 v204, 0xbfcc422a, v204
	v_mul_f32_e32 v205, 0xbfcc422a, v205
	v_mul_f32_e32 v206, 0xbfcc422a, v206
	v_mul_f32_e32 v207, 0xbfcc422a, v207
	v_mul_f32_e32 v204, 0x3fb8aa3b, v204
	v_mul_f32_e32 v205, 0x3fb8aa3b, v205
	v_mul_f32_e32 v206, 0x3fb8aa3b, v206
	v_mul_f32_e32 v207, 0x3fb8aa3b, v207
	v_exp_f32_e32 v204, v204
	v_exp_f32_e32 v205, v205
	v_exp_f32_e32 v206, v206
	v_exp_f32_e32 v207, v207
	v_add_f32_e32 v204, 1.0, v204
	v_add_f32_e32 v205, 1.0, v205
	v_add_f32_e32 v206, 1.0, v206
	v_add_f32_e32 v207, 1.0, v207
	v_rcp_f32_e32 v204, v204
	v_rcp_f32_e32 v205, v205
	v_rcp_f32_e32 v206, v206
	v_rcp_f32_e32 v207, v207
	v_mul_f32_e32 v204, v44, v204
	v_mul_f32_e32 v205, v45, v205
	v_mul_f32_e32 v206, v46, v206
	v_mul_f32_e32 v207, v47, v207
	v_cvt_pk_bf16_f32 v208, v204, v205
	v_cvt_pk_bf16_f32 v209, v206, v207
	v_lshlrev_b32_e32 v0, 12, v198
	v_lshl_add_u64 v[210:211], v[132:133], 0, v[0:1]
	global_store_dwordx2 v[210:211], v[208:209], off
	s_waitcnt vmcnt(15)
	v_lshlrev_b32_e32 v204, 16, v86
	v_and_b32_e32 v205, 0xffff0000, v86
	v_lshlrev_b32_e32 v206, 16, v87
	v_and_b32_e32 v207, 0xffff0000, v87
	v_fma_f32 v40, v4, v204, v40
	v_fma_f32 v41, v5, v205, v41
	v_fma_f32 v42, v6, v206, v42
	v_fma_f32 v43, v7, v207, v43
	v_mul_f32_e32 v204, 0x3d372713, v40
	v_mul_f32_e32 v205, 0x3d372713, v41
	v_mul_f32_e32 v206, 0x3d372713, v42
	v_mul_f32_e32 v207, 0x3d372713, v43
	v_mul_f32_e32 v204, v40, v204
	v_mul_f32_e32 v205, v41, v205
	v_mul_f32_e32 v206, v42, v206
	v_mul_f32_e32 v207, v43, v207
	v_fma_f32 v204, v40, v204, v40
	v_fma_f32 v205, v41, v205, v41
	v_fma_f32 v206, v42, v206, v42
	v_fma_f32 v207, v43, v207, v43
	v_mul_f32_e32 v204, 0xbfcc422a, v204
	v_mul_f32_e32 v205, 0xbfcc422a, v205
	v_mul_f32_e32 v206, 0xbfcc422a, v206
	v_mul_f32_e32 v207, 0xbfcc422a, v207
	v_mul_f32_e32 v204, 0x3fb8aa3b, v204
	v_mul_f32_e32 v205, 0x3fb8aa3b, v205
	v_mul_f32_e32 v206, 0x3fb8aa3b, v206
	v_mul_f32_e32 v207, 0x3fb8aa3b, v207
	v_exp_f32_e32 v204, v204
	v_exp_f32_e32 v205, v205
	v_exp_f32_e32 v206, v206
	v_exp_f32_e32 v207, v207
	v_add_f32_e32 v204, 1.0, v204
	v_add_f32_e32 v205, 1.0, v205
	v_add_f32_e32 v206, 1.0, v206
	v_add_f32_e32 v207, 1.0, v207
	v_rcp_f32_e32 v204, v204
	v_rcp_f32_e32 v205, v205
	v_rcp_f32_e32 v206, v206
	v_rcp_f32_e32 v207, v207
	v_mul_f32_e32 v204, v40, v204
	v_mul_f32_e32 v205, v41, v205
	v_mul_f32_e32 v206, v42, v206
	v_mul_f32_e32 v207, v43, v207
	v_cvt_pk_bf16_f32 v208, v204, v205
	v_cvt_pk_bf16_f32 v209, v206, v207
	v_lshlrev_b32_e32 v0, 12, v197
	v_lshl_add_u64 v[210:211], v[132:133], 0, v[0:1]
	global_store_dwordx2 v[210:211], v[208:209], off
	s_waitcnt vmcnt(15)
	v_lshlrev_b32_e32 v204, 16, v84
	v_and_b32_e32 v205, 0xffff0000, v84
	v_lshlrev_b32_e32 v206, 16, v85
	v_and_b32_e32 v207, 0xffff0000, v85
	v_fma_f32 v36, v4, v204, v36
	v_fma_f32 v37, v5, v205, v37
	v_fma_f32 v38, v6, v206, v38
	v_fma_f32 v39, v7, v207, v39
	v_mul_f32_e32 v204, 0x3d372713, v36
	v_mul_f32_e32 v205, 0x3d372713, v37
	v_mul_f32_e32 v206, 0x3d372713, v38
	v_mul_f32_e32 v207, 0x3d372713, v39
	v_mul_f32_e32 v204, v36, v204
	v_mul_f32_e32 v205, v37, v205
	v_mul_f32_e32 v206, v38, v206
	v_mul_f32_e32 v207, v39, v207
	v_fma_f32 v204, v36, v204, v36
	v_fma_f32 v205, v37, v205, v37
	v_fma_f32 v206, v38, v206, v38
	v_fma_f32 v207, v39, v207, v39
	v_mul_f32_e32 v204, 0xbfcc422a, v204
	v_mul_f32_e32 v205, 0xbfcc422a, v205
	v_mul_f32_e32 v206, 0xbfcc422a, v206
	v_mul_f32_e32 v207, 0xbfcc422a, v207
	v_mul_f32_e32 v204, 0x3fb8aa3b, v204
	v_mul_f32_e32 v205, 0x3fb8aa3b, v205
	v_mul_f32_e32 v206, 0x3fb8aa3b, v206
	v_mul_f32_e32 v207, 0x3fb8aa3b, v207
	v_exp_f32_e32 v204, v204
	v_exp_f32_e32 v205, v205
	v_exp_f32_e32 v206, v206
	v_exp_f32_e32 v207, v207
	v_add_f32_e32 v204, 1.0, v204
	v_add_f32_e32 v205, 1.0, v205
	v_add_f32_e32 v206, 1.0, v206
	v_add_f32_e32 v207, 1.0, v207
	v_rcp_f32_e32 v204, v204
	v_rcp_f32_e32 v205, v205
	v_rcp_f32_e32 v206, v206
	v_rcp_f32_e32 v207, v207
	v_mul_f32_e32 v204, v36, v204
	v_mul_f32_e32 v205, v37, v205
	v_mul_f32_e32 v206, v38, v206
	v_mul_f32_e32 v207, v39, v207
	v_cvt_pk_bf16_f32 v208, v204, v205
	v_cvt_pk_bf16_f32 v209, v206, v207
	v_lshlrev_b32_e32 v0, 12, v196
	v_lshl_add_u64 v[210:211], v[132:133], 0, v[0:1]
	global_store_dwordx2 v[210:211], v[208:209], off
	s_waitcnt vmcnt(15)
	v_lshlrev_b32_e32 v204, 16, v82
	v_and_b32_e32 v205, 0xffff0000, v82
	v_lshlrev_b32_e32 v206, 16, v83
	v_and_b32_e32 v207, 0xffff0000, v83
	v_fma_f32 v32, v4, v204, v32
	v_fma_f32 v33, v5, v205, v33
	v_fma_f32 v34, v6, v206, v34
	v_fma_f32 v35, v7, v207, v35
	v_mul_f32_e32 v204, 0x3d372713, v32
	v_mul_f32_e32 v205, 0x3d372713, v33
	v_mul_f32_e32 v206, 0x3d372713, v34
	v_mul_f32_e32 v207, 0x3d372713, v35
	v_mul_f32_e32 v204, v32, v204
	v_mul_f32_e32 v205, v33, v205
	v_mul_f32_e32 v206, v34, v206
	v_mul_f32_e32 v207, v35, v207
	v_fma_f32 v204, v32, v204, v32
	v_fma_f32 v205, v33, v205, v33
	v_fma_f32 v206, v34, v206, v34
	v_fma_f32 v207, v35, v207, v35
	v_mul_f32_e32 v204, 0xbfcc422a, v204
	v_mul_f32_e32 v205, 0xbfcc422a, v205
	v_mul_f32_e32 v206, 0xbfcc422a, v206
	v_mul_f32_e32 v207, 0xbfcc422a, v207
	v_mul_f32_e32 v204, 0x3fb8aa3b, v204
	v_mul_f32_e32 v205, 0x3fb8aa3b, v205
	v_mul_f32_e32 v206, 0x3fb8aa3b, v206
	v_mul_f32_e32 v207, 0x3fb8aa3b, v207
	v_exp_f32_e32 v204, v204
	v_exp_f32_e32 v205, v205
	v_exp_f32_e32 v206, v206
	v_exp_f32_e32 v207, v207
	v_add_f32_e32 v204, 1.0, v204
	v_add_f32_e32 v205, 1.0, v205
	v_add_f32_e32 v206, 1.0, v206
	v_add_f32_e32 v207, 1.0, v207
	v_rcp_f32_e32 v204, v204
	v_rcp_f32_e32 v205, v205
	v_rcp_f32_e32 v206, v206
	v_rcp_f32_e32 v207, v207
	v_mul_f32_e32 v204, v32, v204
	v_mul_f32_e32 v205, v33, v205
	v_mul_f32_e32 v206, v34, v206
	v_mul_f32_e32 v207, v35, v207
	v_cvt_pk_bf16_f32 v208, v204, v205
	v_cvt_pk_bf16_f32 v209, v206, v207
	v_lshlrev_b32_e32 v0, 12, v195
	v_lshl_add_u64 v[210:211], v[132:133], 0, v[0:1]
	global_store_dwordx2 v[210:211], v[208:209], off
	s_waitcnt vmcnt(15)
	v_lshlrev_b32_e32 v204, 16, v80
	v_and_b32_e32 v205, 0xffff0000, v80
	v_lshlrev_b32_e32 v206, 16, v81
	v_and_b32_e32 v207, 0xffff0000, v81
	v_fma_f32 v28, v4, v204, v28
	v_fma_f32 v29, v5, v205, v29
	v_fma_f32 v30, v6, v206, v30
	v_fma_f32 v31, v7, v207, v31
	v_mul_f32_e32 v204, 0x3d372713, v28
	v_mul_f32_e32 v205, 0x3d372713, v29
	v_mul_f32_e32 v206, 0x3d372713, v30
	v_mul_f32_e32 v207, 0x3d372713, v31
	v_mul_f32_e32 v204, v28, v204
	v_mul_f32_e32 v205, v29, v205
	v_mul_f32_e32 v206, v30, v206
	v_mul_f32_e32 v207, v31, v207
	v_fma_f32 v204, v28, v204, v28
	v_fma_f32 v205, v29, v205, v29
	v_fma_f32 v206, v30, v206, v30
	v_fma_f32 v207, v31, v207, v31
	v_mul_f32_e32 v204, 0xbfcc422a, v204
	v_mul_f32_e32 v205, 0xbfcc422a, v205
	v_mul_f32_e32 v206, 0xbfcc422a, v206
	v_mul_f32_e32 v207, 0xbfcc422a, v207
	v_mul_f32_e32 v204, 0x3fb8aa3b, v204
	v_mul_f32_e32 v205, 0x3fb8aa3b, v205
	v_mul_f32_e32 v206, 0x3fb8aa3b, v206
	v_mul_f32_e32 v207, 0x3fb8aa3b, v207
	v_exp_f32_e32 v204, v204
	v_exp_f32_e32 v205, v205
	v_exp_f32_e32 v206, v206
	v_exp_f32_e32 v207, v207
	v_add_f32_e32 v204, 1.0, v204
	v_add_f32_e32 v205, 1.0, v205
	v_add_f32_e32 v206, 1.0, v206
	v_add_f32_e32 v207, 1.0, v207
	v_rcp_f32_e32 v204, v204
	v_rcp_f32_e32 v205, v205
	v_rcp_f32_e32 v206, v206
	v_rcp_f32_e32 v207, v207
	v_mul_f32_e32 v204, v28, v204
	v_mul_f32_e32 v205, v29, v205
	v_mul_f32_e32 v206, v30, v206
	v_mul_f32_e32 v207, v31, v207
	v_cvt_pk_bf16_f32 v208, v204, v205
	v_cvt_pk_bf16_f32 v209, v206, v207
	v_lshlrev_b32_e32 v0, 12, v194
	v_lshl_add_u64 v[210:211], v[132:133], 0, v[0:1]
	global_store_dwordx2 v[210:211], v[208:209], off
	s_waitcnt vmcnt(15)
	v_lshlrev_b32_e32 v204, 16, v78
	v_and_b32_e32 v205, 0xffff0000, v78
	v_lshlrev_b32_e32 v206, 16, v79
	v_and_b32_e32 v207, 0xffff0000, v79
	v_fma_f32 v24, v4, v204, v24
	v_fma_f32 v25, v5, v205, v25
	v_fma_f32 v26, v6, v206, v26
	v_fma_f32 v27, v7, v207, v27
	v_mul_f32_e32 v204, 0x3d372713, v24
	v_mul_f32_e32 v205, 0x3d372713, v25
	v_mul_f32_e32 v206, 0x3d372713, v26
	v_mul_f32_e32 v207, 0x3d372713, v27
	v_mul_f32_e32 v204, v24, v204
	v_mul_f32_e32 v205, v25, v205
	v_mul_f32_e32 v206, v26, v206
	v_mul_f32_e32 v207, v27, v207
	v_fma_f32 v204, v24, v204, v24
	v_fma_f32 v205, v25, v205, v25
	v_fma_f32 v206, v26, v206, v26
	v_fma_f32 v207, v27, v207, v27
	v_mul_f32_e32 v204, 0xbfcc422a, v204
	v_mul_f32_e32 v205, 0xbfcc422a, v205
	v_mul_f32_e32 v206, 0xbfcc422a, v206
	v_mul_f32_e32 v207, 0xbfcc422a, v207
	v_mul_f32_e32 v204, 0x3fb8aa3b, v204
	v_mul_f32_e32 v205, 0x3fb8aa3b, v205
	v_mul_f32_e32 v206, 0x3fb8aa3b, v206
	v_mul_f32_e32 v207, 0x3fb8aa3b, v207
	v_exp_f32_e32 v204, v204
	v_exp_f32_e32 v205, v205
	v_exp_f32_e32 v206, v206
	v_exp_f32_e32 v207, v207
	v_add_f32_e32 v204, 1.0, v204
	v_add_f32_e32 v205, 1.0, v205
	v_add_f32_e32 v206, 1.0, v206
	v_add_f32_e32 v207, 1.0, v207
	v_rcp_f32_e32 v204, v204
	v_rcp_f32_e32 v205, v205
	v_rcp_f32_e32 v206, v206
	v_rcp_f32_e32 v207, v207
	v_mul_f32_e32 v204, v24, v204
	v_mul_f32_e32 v205, v25, v205
	v_mul_f32_e32 v206, v26, v206
	v_mul_f32_e32 v207, v27, v207
	v_cvt_pk_bf16_f32 v208, v204, v205
	v_cvt_pk_bf16_f32 v209, v206, v207
	v_lshlrev_b32_e32 v0, 12, v193
	v_lshl_add_u64 v[210:211], v[132:133], 0, v[0:1]
	global_store_dwordx2 v[210:211], v[208:209], off
	s_waitcnt vmcnt(15)
	v_lshlrev_b32_e32 v204, 16, v76
	v_and_b32_e32 v205, 0xffff0000, v76
	v_lshlrev_b32_e32 v206, 16, v77
	v_and_b32_e32 v207, 0xffff0000, v77
	v_fma_f32 v20, v4, v204, v20
	v_fma_f32 v21, v5, v205, v21
	v_fma_f32 v22, v6, v206, v22
	v_fma_f32 v23, v7, v207, v23
	v_mul_f32_e32 v204, 0x3d372713, v20
	v_mul_f32_e32 v205, 0x3d372713, v21
	v_mul_f32_e32 v206, 0x3d372713, v22
	v_mul_f32_e32 v207, 0x3d372713, v23
	v_mul_f32_e32 v204, v20, v204
	v_mul_f32_e32 v205, v21, v205
	v_mul_f32_e32 v206, v22, v206
	v_mul_f32_e32 v207, v23, v207
	v_fma_f32 v204, v20, v204, v20
	v_fma_f32 v205, v21, v205, v21
	v_fma_f32 v206, v22, v206, v22
	v_fma_f32 v207, v23, v207, v23
	v_mul_f32_e32 v204, 0xbfcc422a, v204
	v_mul_f32_e32 v205, 0xbfcc422a, v205
	v_mul_f32_e32 v206, 0xbfcc422a, v206
	v_mul_f32_e32 v207, 0xbfcc422a, v207
	v_mul_f32_e32 v204, 0x3fb8aa3b, v204
	v_mul_f32_e32 v205, 0x3fb8aa3b, v205
	v_mul_f32_e32 v206, 0x3fb8aa3b, v206
	v_mul_f32_e32 v207, 0x3fb8aa3b, v207
	v_exp_f32_e32 v204, v204
	v_exp_f32_e32 v205, v205
	v_exp_f32_e32 v206, v206
	v_exp_f32_e32 v207, v207
	v_add_f32_e32 v204, 1.0, v204
	v_add_f32_e32 v205, 1.0, v205
	v_add_f32_e32 v206, 1.0, v206
	v_add_f32_e32 v207, 1.0, v207
	v_rcp_f32_e32 v204, v204
	v_rcp_f32_e32 v205, v205
	v_rcp_f32_e32 v206, v206
	v_rcp_f32_e32 v207, v207
	v_mul_f32_e32 v204, v20, v204
	v_mul_f32_e32 v205, v21, v205
	v_mul_f32_e32 v206, v22, v206
	v_mul_f32_e32 v207, v23, v207
	v_cvt_pk_bf16_f32 v208, v204, v205
	v_cvt_pk_bf16_f32 v209, v206, v207
	v_lshlrev_b32_e32 v0, 12, v123
	v_lshl_add_u64 v[210:211], v[132:133], 0, v[0:1]
	global_store_dwordx2 v[210:211], v[208:209], off
	s_waitcnt vmcnt(15)
	v_lshlrev_b32_e32 v204, 16, v74
	v_and_b32_e32 v205, 0xffff0000, v74
	v_lshlrev_b32_e32 v206, 16, v75
	v_and_b32_e32 v207, 0xffff0000, v75
	v_fma_f32 v16, v4, v204, v16
	v_fma_f32 v17, v5, v205, v17
	v_fma_f32 v18, v6, v206, v18
	v_fma_f32 v19, v7, v207, v19
	v_mul_f32_e32 v204, 0x3d372713, v16
	v_mul_f32_e32 v205, 0x3d372713, v17
	v_mul_f32_e32 v206, 0x3d372713, v18
	v_mul_f32_e32 v207, 0x3d372713, v19
	v_mul_f32_e32 v204, v16, v204
	v_mul_f32_e32 v205, v17, v205
	v_mul_f32_e32 v206, v18, v206
	v_mul_f32_e32 v207, v19, v207
	v_fma_f32 v204, v16, v204, v16
	v_fma_f32 v205, v17, v205, v17
	v_fma_f32 v206, v18, v206, v18
	v_fma_f32 v207, v19, v207, v19
	v_mul_f32_e32 v204, 0xbfcc422a, v204
	v_mul_f32_e32 v205, 0xbfcc422a, v205
	v_mul_f32_e32 v206, 0xbfcc422a, v206
	v_mul_f32_e32 v207, 0xbfcc422a, v207
	v_mul_f32_e32 v204, 0x3fb8aa3b, v204
	v_mul_f32_e32 v205, 0x3fb8aa3b, v205
	v_mul_f32_e32 v206, 0x3fb8aa3b, v206
	v_mul_f32_e32 v207, 0x3fb8aa3b, v207
	v_exp_f32_e32 v204, v204
	v_exp_f32_e32 v205, v205
	v_exp_f32_e32 v206, v206
	v_exp_f32_e32 v207, v207
	v_add_f32_e32 v204, 1.0, v204
	v_add_f32_e32 v205, 1.0, v205
	v_add_f32_e32 v206, 1.0, v206
	v_add_f32_e32 v207, 1.0, v207
	v_rcp_f32_e32 v204, v204
	v_rcp_f32_e32 v205, v205
	v_rcp_f32_e32 v206, v206
	v_rcp_f32_e32 v207, v207
	v_mul_f32_e32 v204, v16, v204
	v_mul_f32_e32 v205, v17, v205
	v_mul_f32_e32 v206, v18, v206
	v_mul_f32_e32 v207, v19, v207
	v_cvt_pk_bf16_f32 v208, v204, v205
	v_cvt_pk_bf16_f32 v209, v206, v207
	v_lshlrev_b32_e32 v0, 12, v121
	v_lshl_add_u64 v[210:211], v[132:133], 0, v[0:1]
	global_store_dwordx2 v[210:211], v[208:209], off
	s_waitcnt vmcnt(15)
	v_lshlrev_b32_e32 v204, 16, v72
	v_and_b32_e32 v205, 0xffff0000, v72
	v_lshlrev_b32_e32 v206, 16, v73
	v_and_b32_e32 v207, 0xffff0000, v73
	v_fma_f32 v12, v4, v204, v12
	v_fma_f32 v13, v5, v205, v13
	v_fma_f32 v14, v6, v206, v14
	v_fma_f32 v15, v7, v207, v15
	v_mul_f32_e32 v204, 0x3d372713, v12
	v_mul_f32_e32 v205, 0x3d372713, v13
	v_mul_f32_e32 v206, 0x3d372713, v14
	v_mul_f32_e32 v207, 0x3d372713, v15
	v_mul_f32_e32 v204, v12, v204
	v_mul_f32_e32 v205, v13, v205
	v_mul_f32_e32 v206, v14, v206
	v_mul_f32_e32 v207, v15, v207
	v_fma_f32 v204, v12, v204, v12
	v_fma_f32 v205, v13, v205, v13
	v_fma_f32 v206, v14, v206, v14
	v_fma_f32 v207, v15, v207, v15
	v_mul_f32_e32 v204, 0xbfcc422a, v204
	v_mul_f32_e32 v205, 0xbfcc422a, v205
	v_mul_f32_e32 v206, 0xbfcc422a, v206
	v_mul_f32_e32 v207, 0xbfcc422a, v207
	v_mul_f32_e32 v204, 0x3fb8aa3b, v204
	v_mul_f32_e32 v205, 0x3fb8aa3b, v205
	v_mul_f32_e32 v206, 0x3fb8aa3b, v206
	v_mul_f32_e32 v207, 0x3fb8aa3b, v207
	v_exp_f32_e32 v204, v204
	v_exp_f32_e32 v205, v205
	v_exp_f32_e32 v206, v206
	v_exp_f32_e32 v207, v207
	v_add_f32_e32 v204, 1.0, v204
	v_add_f32_e32 v205, 1.0, v205
	v_add_f32_e32 v206, 1.0, v206
	v_add_f32_e32 v207, 1.0, v207
	v_rcp_f32_e32 v204, v204
	v_rcp_f32_e32 v205, v205
	v_rcp_f32_e32 v206, v206
	v_rcp_f32_e32 v207, v207
	v_mul_f32_e32 v204, v12, v204
	v_mul_f32_e32 v205, v13, v205
	v_mul_f32_e32 v206, v14, v206
	v_mul_f32_e32 v207, v15, v207
	v_cvt_pk_bf16_f32 v208, v204, v205
	v_cvt_pk_bf16_f32 v209, v206, v207
	v_lshlrev_b32_e32 v0, 12, v103
	v_lshl_add_u64 v[210:211], v[132:133], 0, v[0:1]
	global_store_dwordx2 v[210:211], v[208:209], off
	s_waitcnt vmcnt(15)
	v_lshlrev_b32_e32 v204, 16, v2
	v_and_b32_e32 v205, 0xffff0000, v2
	v_lshlrev_b32_e32 v206, 16, v3
	v_and_b32_e32 v207, 0xffff0000, v3
	v_fma_f32 v8, v4, v204, v8
	v_fma_f32 v9, v5, v205, v9
	v_fma_f32 v10, v6, v206, v10
	v_fma_f32 v11, v7, v207, v11
	v_mul_f32_e32 v204, 0x3d372713, v8
	v_mul_f32_e32 v205, 0x3d372713, v9
	v_mul_f32_e32 v206, 0x3d372713, v10
	v_mul_f32_e32 v207, 0x3d372713, v11
	v_mul_f32_e32 v204, v8, v204
	v_mul_f32_e32 v205, v9, v205
	v_mul_f32_e32 v206, v10, v206
	v_mul_f32_e32 v207, v11, v207
	v_fma_f32 v204, v8, v204, v8
	v_fma_f32 v205, v9, v205, v9
	v_fma_f32 v206, v10, v206, v10
	v_fma_f32 v207, v11, v207, v11
	v_mul_f32_e32 v204, 0xbfcc422a, v204
	v_mul_f32_e32 v205, 0xbfcc422a, v205
	v_mul_f32_e32 v206, 0xbfcc422a, v206
	v_mul_f32_e32 v207, 0xbfcc422a, v207
	v_mul_f32_e32 v204, 0x3fb8aa3b, v204
	v_mul_f32_e32 v205, 0x3fb8aa3b, v205
	v_mul_f32_e32 v206, 0x3fb8aa3b, v206
	v_mul_f32_e32 v207, 0x3fb8aa3b, v207
	v_exp_f32_e32 v204, v204
	v_exp_f32_e32 v205, v205
	v_exp_f32_e32 v206, v206
	v_exp_f32_e32 v207, v207
	v_add_f32_e32 v204, 1.0, v204
	v_add_f32_e32 v205, 1.0, v205
	v_add_f32_e32 v206, 1.0, v206
	v_add_f32_e32 v207, 1.0, v207
	v_rcp_f32_e32 v204, v204
	v_rcp_f32_e32 v205, v205
	v_rcp_f32_e32 v206, v206
	v_rcp_f32_e32 v207, v207
	v_mul_f32_e32 v204, v8, v204
	v_mul_f32_e32 v205, v9, v205
	v_mul_f32_e32 v206, v10, v206
	v_mul_f32_e32 v207, v11, v207
	v_cvt_pk_bf16_f32 v208, v204, v205
	v_cvt_pk_bf16_f32 v209, v206, v207
	v_lshlrev_b32_e32 v0, 12, v102
	v_lshl_add_u64 v[210:211], v[132:133], 0, v[0:1]
	global_store_dwordx2 v[210:211], v[208:209], off
	s_cbranch_scc1 .LBB0_149

.Lmy_x3_tri:
	s_waitcnt lgkmcnt(0)
	s_add_i32 s6, s20, 7
	v_lshl_or_b32 v0, s6, 14, v157
	v_lshl_add_u64 v[2:3], v[126:127], 0, v[0:1]
	global_load_dwordx4 v[200:203], v[2:3], off
	s_waitcnt vmcnt(7)
	v_mfma_f32_16x16x32_bf16 v[72:75], v[204:207], v[92:95], v[72:75]
	v_mfma_f32_16x16x32_bf16 v[68:71], v[208:211], v[92:95], v[68:71]
	v_mfma_f32_16x16x32_bf16 v[64:67], v[212:215], v[92:95], v[64:67]
	v_mfma_f32_16x16x32_bf16 v[60:63], v[216:219], v[92:95], v[60:63]
	v_mfma_f32_16x16x32_bf16 v[56:59], v[220:223], v[92:95], v[56:59]
	v_mfma_f32_16x16x32_bf16 v[52:55], v[224:227], v[92:95], v[52:55]
	v_mfma_f32_16x16x32_bf16 v[48:51], v[228:231], v[92:95], v[48:51]
	v_mfma_f32_16x16x32_bf16 v[40:43], v[232:235], v[92:95], v[40:43]
	v_mfma_f32_16x16x32_bf16 v[36:39], v[236:239], v[92:95], v[36:39]
	v_mfma_f32_16x16x32_bf16 v[32:35], v[240:243], v[92:95], v[32:35]
	v_mfma_f32_16x16x32_bf16 v[28:31], v[244:247], v[92:95], v[28:31]
	v_mfma_f32_16x16x32_bf16 v[24:27], v[248:251], v[92:95], v[24:27]
	v_mfma_f32_16x16x32_bf16 v[20:23], v[76:79], v[92:95], v[20:23]
	v_mfma_f32_16x16x32_bf16 v[16:19], v[80:83], v[92:95], v[16:19]
	v_mfma_f32_16x16x32_bf16 v[12:15], v[84:87], v[92:95], v[12:15]
	v_mfma_f32_16x16x32_bf16 v[8:11], v[88:91], v[92:95], v[8:11]
	s_waitcnt vmcnt(6)
	global_load_dwordx4 v[92:95], v[134:135], off
	v_mfma_f32_16x16x32_bf16 v[64:67], v[204:207], v[96:99], v[64:67]
	v_mfma_f32_16x16x32_bf16 v[60:63], v[208:211], v[96:99], v[60:63]
	v_mfma_f32_16x16x32_bf16 v[56:59], v[212:215], v[96:99], v[56:59]
	v_mfma_f32_16x16x32_bf16 v[52:55], v[216:219], v[96:99], v[52:55]
	v_mfma_f32_16x16x32_bf16 v[48:51], v[220:223], v[96:99], v[48:51]
	v_mfma_f32_16x16x32_bf16 v[40:43], v[224:227], v[96:99], v[40:43]
	v_mfma_f32_16x16x32_bf16 v[36:39], v[228:231], v[96:99], v[36:39]
	v_mfma_f32_16x16x32_bf16 v[32:35], v[232:235], v[96:99], v[32:35]
	v_mfma_f32_16x16x32_bf16 v[28:31], v[236:239], v[96:99], v[28:31]
	v_mfma_f32_16x16x32_bf16 v[24:27], v[240:243], v[96:99], v[24:27]
	v_mfma_f32_16x16x32_bf16 v[20:23], v[244:247], v[96:99], v[20:23]
	v_mfma_f32_16x16x32_bf16 v[16:19], v[248:251], v[96:99], v[16:19]
	v_mfma_f32_16x16x32_bf16 v[12:15], v[76:79], v[96:99], v[12:15]
	v_mfma_f32_16x16x32_bf16 v[8:11], v[80:83], v[96:99], v[8:11]
	s_waitcnt vmcnt(6)
	global_load_dwordx4 v[96:99], v[134:135], off offset:64
	v_mfma_f32_16x16x32_bf16 v[56:59], v[204:207], v[100:103], v[56:59]
	v_mfma_f32_16x16x32_bf16 v[52:55], v[208:211], v[100:103], v[52:55]
	v_mfma_f32_16x16x32_bf16 v[48:51], v[212:215], v[100:103], v[48:51]
	v_mfma_f32_16x16x32_bf16 v[40:43], v[216:219], v[100:103], v[40:43]
	v_mfma_f32_16x16x32_bf16 v[36:39], v[220:223], v[100:103], v[36:39]
	v_mfma_f32_16x16x32_bf16 v[32:35], v[224:227], v[100:103], v[32:35]
	v_mfma_f32_16x16x32_bf16 v[28:31], v[228:231], v[100:103], v[28:31]
	v_mfma_f32_16x16x32_bf16 v[24:27], v[232:235], v[100:103], v[24:27]
	v_mfma_f32_16x16x32_bf16 v[20:23], v[236:239], v[100:103], v[20:23]
	v_mfma_f32_16x16x32_bf16 v[16:19], v[240:243], v[100:103], v[16:19]
	v_mfma_f32_16x16x32_bf16 v[12:15], v[244:247], v[100:103], v[12:15]
	v_mfma_f32_16x16x32_bf16 v[8:11], v[248:251], v[100:103], v[8:11]
	s_waitcnt vmcnt(6)
	global_load_dwordx4 v[100:103], v[134:135], off offset:128
	v_mfma_f32_16x16x32_bf16 v[48:51], v[204:207], v[44:47], v[48:51]
	v_mfma_f32_16x16x32_bf16 v[40:43], v[208:211], v[44:47], v[40:43]
	v_mfma_f32_16x16x32_bf16 v[36:39], v[212:215], v[44:47], v[36:39]
	v_mfma_f32_16x16x32_bf16 v[32:35], v[216:219], v[44:47], v[32:35]
	v_mfma_f32_16x16x32_bf16 v[28:31], v[220:223], v[44:47], v[28:31]
	v_mfma_f32_16x16x32_bf16 v[24:27], v[224:227], v[44:47], v[24:27]
	v_mfma_f32_16x16x32_bf16 v[20:23], v[228:231], v[44:47], v[20:23]
	v_mfma_f32_16x16x32_bf16 v[16:19], v[232:235], v[44:47], v[16:19]
	v_mfma_f32_16x16x32_bf16 v[12:15], v[236:239], v[44:47], v[12:15]
	v_mfma_f32_16x16x32_bf16 v[8:11], v[240:243], v[44:47], v[8:11]
	s_waitcnt vmcnt(6)
	v_mfma_f32_16x16x32_bf16 v[36:39], v[204:207], v[136:139], v[36:39]
	v_mfma_f32_16x16x32_bf16 v[32:35], v[208:211], v[136:139], v[32:35]
	v_mfma_f32_16x16x32_bf16 v[28:31], v[212:215], v[136:139], v[28:31]
	v_mfma_f32_16x16x32_bf16 v[24:27], v[216:219], v[136:139], v[24:27]
	v_mfma_f32_16x16x32_bf16 v[20:23], v[220:223], v[136:139], v[20:23]
	v_mfma_f32_16x16x32_bf16 v[16:19], v[224:227], v[136:139], v[16:19]
	v_mfma_f32_16x16x32_bf16 v[12:15], v[228:231], v[136:139], v[12:15]
	v_mfma_f32_16x16x32_bf16 v[8:11], v[232:235], v[136:139], v[8:11]
	s_waitcnt vmcnt(5)
	global_load_dwordx4 v[136:139], v[134:135], off offset:192
	v_mfma_f32_16x16x32_bf16 v[28:31], v[204:207], v[140:143], v[28:31]
	v_mfma_f32_16x16x32_bf16 v[24:27], v[208:211], v[140:143], v[24:27]
	v_mfma_f32_16x16x32_bf16 v[20:23], v[212:215], v[140:143], v[20:23]
	v_mfma_f32_16x16x32_bf16 v[16:19], v[216:219], v[140:143], v[16:19]
	v_mfma_f32_16x16x32_bf16 v[12:15], v[220:223], v[140:143], v[12:15]
	v_mfma_f32_16x16x32_bf16 v[8:11], v[224:227], v[140:143], v[8:11]
	s_waitcnt vmcnt(5)
	v_mfma_f32_16x16x32_bf16 v[20:23], v[204:207], v[196:199], v[20:23]
	v_mfma_f32_16x16x32_bf16 v[16:19], v[208:211], v[196:199], v[16:19]
	v_mfma_f32_16x16x32_bf16 v[12:15], v[212:215], v[196:199], v[12:15]
	v_mfma_f32_16x16x32_bf16 v[8:11], v[216:219], v[196:199], v[8:11]
	s_waitcnt vmcnt(4)
	v_mfma_f32_16x16x32_bf16 v[12:15], v[204:207], v[200:203], v[12:15]
	v_mfma_f32_16x16x32_bf16 v[8:11], v[208:211], v[200:203], v[8:11]
	v_add_u32_e32 v194, v179, v162
	v_add_u32_e32 v195, 0x8800, v194
	ds_read_b128 v[228:231], v194 offset:59392
	ds_read_b128 v[232:235], v194 offset:63744
	ds_read_b128 v[224:227], v194 offset:55040
	ds_read_b128 v[236:239], v195 offset:33280
	ds_read_b128 v[220:223], v194 offset:50688
	ds_read_b128 v[240:243], v195 offset:37632
	ds_read_b128 v[216:219], v194 offset:46336
	ds_read_b128 v[244:247], v195 offset:41984
	ds_read_b128 v[212:215], v194 offset:41984
	ds_read_b128 v[248:251], v195 offset:46336
	ds_read_b128 v[208:211], v194 offset:37632
	ds_read_b128 v[76:79], v195 offset:50688
	ds_read_b128 v[204:207], v194 offset:33280
	ds_read_b128 v[80:83], v195 offset:55040
	ds_read_b128 v[84:87], v195 offset:59392
	ds_read_b128 v[88:91], v195 offset:63744
	s_waitcnt vmcnt(3)
	s_waitcnt lgkmcnt(15)
	v_mfma_f32_16x16x32_bf16 v[48:51], v[228:231], v[92:95], v[48:51]
	ds_read_b128 v[228:231], v194 offset:59456
	s_waitcnt lgkmcnt(15)
	v_mfma_f32_16x16x32_bf16 v[40:43], v[232:235], v[92:95], v[40:43]
	ds_read_b128 v[232:235], v194 offset:63808
	s_waitcnt lgkmcnt(15)
	v_mfma_f32_16x16x32_bf16 v[52:55], v[224:227], v[92:95], v[52:55]
	ds_read_b128 v[224:227], v194 offset:55104
	s_waitcnt lgkmcnt(15)
	v_mfma_f32_16x16x32_bf16 v[36:39], v[236:239], v[92:95], v[36:39]
	ds_read_b128 v[236:239], v195 offset:33344
	s_waitcnt lgkmcnt(15)
	v_mfma_f32_16x16x32_bf16 v[56:59], v[220:223], v[92:95], v[56:59]
	ds_read_b128 v[220:223], v194 offset:50752
	s_waitcnt lgkmcnt(15)
	v_mfma_f32_16x16x32_bf16 v[32:35], v[240:243], v[92:95], v[32:35]
	ds_read_b128 v[240:243], v195 offset:37696
	s_waitcnt lgkmcnt(15)
	v_mfma_f32_16x16x32_bf16 v[60:63], v[216:219], v[92:95], v[60:63]
	ds_read_b128 v[216:219], v194 offset:46400
	s_waitcnt lgkmcnt(15)
	v_mfma_f32_16x16x32_bf16 v[28:31], v[244:247], v[92:95], v[28:31]
	ds_read_b128 v[244:247], v195 offset:42048
	s_waitcnt lgkmcnt(15)
	v_mfma_f32_16x16x32_bf16 v[64:67], v[212:215], v[92:95], v[64:67]
	ds_read_b128 v[212:215], v194 offset:42048
	s_waitcnt lgkmcnt(15)
	v_mfma_f32_16x16x32_bf16 v[24:27], v[248:251], v[92:95], v[24:27]
	ds_read_b128 v[248:251], v195 offset:46400
	s_waitcnt lgkmcnt(15)
	v_mfma_f32_16x16x32_bf16 v[68:71], v[208:211], v[92:95], v[68:71]
	ds_read_b128 v[208:211], v194 offset:37696
	s_waitcnt lgkmcnt(15)
	v_mfma_f32_16x16x32_bf16 v[20:23], v[76:79], v[92:95], v[20:23]
	ds_read_b128 v[76:79], v195 offset:50752
	s_waitcnt lgkmcnt(15)
	v_mfma_f32_16x16x32_bf16 v[72:75], v[204:207], v[92:95], v[72:75]
	ds_read_b128 v[204:207], v194 offset:33344
	s_waitcnt lgkmcnt(15)
	v_mfma_f32_16x16x32_bf16 v[16:19], v[80:83], v[92:95], v[16:19]
	ds_read_b128 v[80:83], v195 offset:55104
	s_waitcnt lgkmcnt(15)
	v_mfma_f32_16x16x32_bf16 v[12:15], v[84:87], v[92:95], v[12:15]
	ds_read_b128 v[84:87], v195 offset:59456
	s_waitcnt lgkmcnt(15)
	v_mfma_f32_16x16x32_bf16 v[8:11], v[88:91], v[92:95], v[8:11]
	ds_read_b128 v[88:91], v195 offset:63808
	s_waitcnt vmcnt(2)
	s_waitcnt lgkmcnt(15)
	v_mfma_f32_16x16x32_bf16 v[48:51], v[228:231], v[96:99], v[48:51]
	ds_read_b128 v[228:231], v194 offset:59520
	s_waitcnt lgkmcnt(15)
	v_mfma_f32_16x16x32_bf16 v[40:43], v[232:235], v[96:99], v[40:43]
	ds_read_b128 v[232:235], v194 offset:63872
	s_waitcnt lgkmcnt(15)
	v_mfma_f32_16x16x32_bf16 v[52:55], v[224:227], v[96:99], v[52:55]
	ds_read_b128 v[224:227], v194 offset:55168
	s_waitcnt lgkmcnt(15)
	v_mfma_f32_16x16x32_bf16 v[36:39], v[236:239], v[96:99], v[36:39]
	ds_read_b128 v[236:239], v195 offset:33408
	s_waitcnt lgkmcnt(15)
	v_mfma_f32_16x16x32_bf16 v[56:59], v[220:223], v[96:99], v[56:59]
	ds_read_b128 v[220:223], v194 offset:50816
	s_waitcnt lgkmcnt(15)
	v_mfma_f32_16x16x32_bf16 v[32:35], v[240:243], v[96:99], v[32:35]
	ds_read_b128 v[240:243], v195 offset:37760
	s_waitcnt lgkmcnt(15)
	v_mfma_f32_16x16x32_bf16 v[60:63], v[216:219], v[96:99], v[60:63]
	ds_read_b128 v[216:219], v194 offset:46464
	s_waitcnt lgkmcnt(15)
	v_mfma_f32_16x16x32_bf16 v[28:31], v[244:247], v[96:99], v[28:31]
	ds_read_b128 v[244:247], v195 offset:42112
	s_waitcnt lgkmcnt(15)
	v_mfma_f32_16x16x32_bf16 v[64:67], v[212:215], v[96:99], v[64:67]
	ds_read_b128 v[212:215], v194 offset:42112
	s_waitcnt lgkmcnt(15)
	v_mfma_f32_16x16x32_bf16 v[24:27], v[248:251], v[96:99], v[24:27]
	ds_read_b128 v[248:251], v195 offset:46464
	s_waitcnt lgkmcnt(15)
	v_mfma_f32_16x16x32_bf16 v[68:71], v[208:211], v[96:99], v[68:71]
	ds_read_b128 v[208:211], v194 offset:37760
	s_waitcnt lgkmcnt(15)
	v_mfma_f32_16x16x32_bf16 v[20:23], v[76:79], v[96:99], v[20:23]
	ds_read_b128 v[76:79], v195 offset:50816
	s_waitcnt lgkmcnt(15)
	v_mfma_f32_16x16x32_bf16 v[72:75], v[204:207], v[96:99], v[72:75]
	ds_read_b128 v[204:207], v194 offset:33408
	s_waitcnt lgkmcnt(15)
	v_mfma_f32_16x16x32_bf16 v[16:19], v[80:83], v[96:99], v[16:19]
	ds_read_b128 v[80:83], v195 offset:55168
	s_waitcnt lgkmcnt(15)
	v_mfma_f32_16x16x32_bf16 v[12:15], v[84:87], v[96:99], v[12:15]
	ds_read_b128 v[84:87], v195 offset:59520
	s_waitcnt lgkmcnt(15)
	v_mfma_f32_16x16x32_bf16 v[8:11], v[88:91], v[96:99], v[8:11]
	ds_read_b128 v[88:91], v195 offset:63872
	s_waitcnt vmcnt(1)
	s_waitcnt lgkmcnt(15)
	v_mfma_f32_16x16x32_bf16 v[48:51], v[228:231], v[100:103], v[48:51]
	ds_read_b128 v[228:231], v194 offset:59584
	s_waitcnt lgkmcnt(15)
	v_mfma_f32_16x16x32_bf16 v[40:43], v[232:235], v[100:103], v[40:43]
	ds_read_b128 v[232:235], v194 offset:63936
	s_waitcnt lgkmcnt(15)
	v_mfma_f32_16x16x32_bf16 v[52:55], v[224:227], v[100:103], v[52:55]
	ds_read_b128 v[224:227], v194 offset:55232
	s_waitcnt lgkmcnt(15)
	v_mfma_f32_16x16x32_bf16 v[36:39], v[236:239], v[100:103], v[36:39]
	ds_read_b128 v[236:239], v195 offset:33472
	s_waitcnt lgkmcnt(15)
	v_mfma_f32_16x16x32_bf16 v[56:59], v[220:223], v[100:103], v[56:59]
	ds_read_b128 v[220:223], v194 offset:50880
	s_waitcnt lgkmcnt(15)
	v_mfma_f32_16x16x32_bf16 v[32:35], v[240:243], v[100:103], v[32:35]
	ds_read_b128 v[240:243], v195 offset:37824
	s_waitcnt lgkmcnt(15)
	v_mfma_f32_16x16x32_bf16 v[60:63], v[216:219], v[100:103], v[60:63]
	ds_read_b128 v[216:219], v194 offset:46528
	s_waitcnt lgkmcnt(15)
	v_mfma_f32_16x16x32_bf16 v[28:31], v[244:247], v[100:103], v[28:31]
	ds_read_b128 v[244:247], v195 offset:42176
	s_waitcnt lgkmcnt(15)
	v_mfma_f32_16x16x32_bf16 v[64:67], v[212:215], v[100:103], v[64:67]
	ds_read_b128 v[212:215], v194 offset:42176
	s_waitcnt lgkmcnt(15)
	v_mfma_f32_16x16x32_bf16 v[24:27], v[248:251], v[100:103], v[24:27]
	ds_read_b128 v[248:251], v195 offset:46528
	s_waitcnt lgkmcnt(15)
	v_mfma_f32_16x16x32_bf16 v[68:71], v[208:211], v[100:103], v[68:71]
	ds_read_b128 v[208:211], v194 offset:37824
	s_waitcnt lgkmcnt(15)
	v_mfma_f32_16x16x32_bf16 v[20:23], v[76:79], v[100:103], v[20:23]
	ds_read_b128 v[76:79], v195 offset:50880
	s_waitcnt lgkmcnt(15)
	v_mfma_f32_16x16x32_bf16 v[72:75], v[204:207], v[100:103], v[72:75]
	ds_read_b128 v[204:207], v194 offset:33472
	s_waitcnt lgkmcnt(15)
	v_mfma_f32_16x16x32_bf16 v[16:19], v[80:83], v[100:103], v[16:19]
	ds_read_b128 v[80:83], v195 offset:55232
	s_waitcnt lgkmcnt(15)
	v_mfma_f32_16x16x32_bf16 v[12:15], v[84:87], v[100:103], v[12:15]
	ds_read_b128 v[84:87], v195 offset:59584
	s_waitcnt lgkmcnt(15)
	v_mfma_f32_16x16x32_bf16 v[8:11], v[88:91], v[100:103], v[8:11]
	ds_read_b128 v[88:91], v195 offset:63936
	s_waitcnt vmcnt(0)
	s_waitcnt lgkmcnt(15)
	v_mfma_f32_16x16x32_bf16 v[44:47], v[228:231], v[136:139], v[48:51]
	s_waitcnt lgkmcnt(14)
	v_mfma_f32_16x16x32_bf16 v[40:43], v[232:235], v[136:139], v[40:43]
	s_waitcnt lgkmcnt(13)
	v_mfma_f32_16x16x32_bf16 v[48:51], v[224:227], v[136:139], v[52:55]
	s_waitcnt lgkmcnt(12)
	v_mfma_f32_16x16x32_bf16 v[36:39], v[236:239], v[136:139], v[36:39]
	s_waitcnt lgkmcnt(11)
	v_mfma_f32_16x16x32_bf16 v[52:55], v[220:223], v[136:139], v[56:59]
	s_waitcnt lgkmcnt(10)
	v_mfma_f32_16x16x32_bf16 v[32:35], v[240:243], v[136:139], v[32:35]
	s_waitcnt lgkmcnt(9)
	v_mfma_f32_16x16x32_bf16 v[56:59], v[216:219], v[136:139], v[60:63]
	s_waitcnt lgkmcnt(8)
	v_mfma_f32_16x16x32_bf16 v[28:31], v[244:247], v[136:139], v[28:31]
	s_waitcnt lgkmcnt(7)
	v_mfma_f32_16x16x32_bf16 v[60:63], v[212:215], v[136:139], v[64:67]
	s_waitcnt lgkmcnt(6)
	v_mfma_f32_16x16x32_bf16 v[24:27], v[248:251], v[136:139], v[24:27]
	s_waitcnt lgkmcnt(5)
	v_mfma_f32_16x16x32_bf16 v[64:67], v[208:211], v[136:139], v[68:71]
	s_waitcnt lgkmcnt(4)
	v_mfma_f32_16x16x32_bf16 v[20:23], v[76:79], v[136:139], v[20:23]
	s_waitcnt lgkmcnt(3)
	v_mfma_f32_16x16x32_bf16 v[68:71], v[204:207], v[136:139], v[72:75]
	s_waitcnt lgkmcnt(2)
	v_mfma_f32_16x16x32_bf16 v[16:19], v[80:83], v[136:139], v[16:19]
	s_waitcnt lgkmcnt(1)
	v_mfma_f32_16x16x32_bf16 v[12:15], v[84:87], v[136:139], v[12:15]
	s_waitcnt lgkmcnt(0)
	v_mfma_f32_16x16x32_bf16 v[8:11], v[88:91], v[136:139], v[8:11]
	v_add_u32_e32 v148, s12, v192
	v_or_b32_e32 v203, 1, v148
	v_or_b32_e32 v202, 2, v148
	v_or_b32_e32 v201, 3, v148
	v_or_b32_e32 v200, 4, v148
	v_or_b32_e32 v199, 5, v148
	v_or_b32_e32 v198, 6, v148
	v_or_b32_e32 v197, 7, v148
	v_or_b32_e32 v196, 8, v148
	v_or_b32_e32 v195, 9, v148
	v_or_b32_e32 v194, 10, v148
	v_or_b32_e32 v193, 11, v148
	v_or_b32_e32 v123, 12, v148
	v_or_b32_e32 v121, 13, v148
	v_or_b32_e32 v103, 14, v148
	v_or_b32_e32 v102, 15, v148
	s_add_i32 s11, s11, 1
	v_add_u32_e32 v119, 0x2000, v119
	s_cmp_eq_u32 s11, 4
	v_lshlrev_b32_e32 v0, 13, v148
	v_lshl_add_u64 v[2:3], v[128:129], 0, v[0:1]
	global_load_dwordx2 v[100:101], v[2:3], off
	v_lshlrev_b32_e32 v0, 13, v203
	v_lshl_add_u64 v[2:3], v[128:129], 0, v[0:1]
	v_lshlrev_b32_e32 v0, 13, v202
	s_branch .Lmy_x3_epi
